# nt (non-temporal) hint on the 32 f32 new_k/new_v prompt-row output stores of the QKV epilogue; on top of e1,e4,e6,e10,e11
# baseline (speedup 1.0000x reference)
; __device__ __forceinline__ u32x4 pack8(f32x4 a, f32x4 b) { u32x4 w; w.x = cvt_pk_bf16(a[0], a[1]); w.y = cvt_pk_bf16(a[2], a[3]); w.z = cvt_pk_bf16(b[0], b[1]); w.w = cvt_pk_bf16(b[2], b[3]); return w; }
;     __device__ __forceinline__ void operator()(const f32x4 (&acc)[2][2][4][2], const Unit& u, int wr, int wc, int fr, int fq, const float (&rsv)[2][4]) const {
;         const int seg = u.pn >> 3, row0 = u.pm * BM + wr * 64 + fr, col0 = (u.pn & 7) * BM + wc * 32 + 8 * fq;
;         bf16_t* dst = (bf16_t*)((char*)Q + (size_t)(seg + (seg >> 1)) * (65 * MiB));
;         const bool smp = u.pm >= 64; const int frow0 = smp ? row0 - MP : row0;
;         float* fo = out + (smp ? OFF_K_S : OFF_K_P) + (size_t)(seg ? seg - 1 : 0) * (smp ? (OFF_V_S - OFF_K_S) : (OFF_V_P - OFF_K_P));
; #pragma unroll
;         for (int ai = 0; ai < 2; ++ai)
; #pragma unroll
;             for (int m = 0; m < 4; ++m) { const int row = row0 + ai * HALF + m * 16; const float rs = rsv[ai][m];
; #pragma unroll
;                 for (int bj = 0; bj < 2; ++bj) { const f32x4 a = acc[ai][bj][m][0] * rs, b = acc[ai][bj][m][1] * rs; const size_t off = (size_t)row * D + col0 + bj * HALF;
;                     *(u32x4*)(dst + off) = pack8(a, b);
;                     if (seg) { float* p = fo + (size_t)(frow0 + ai * HALF + m * 16) * D + col0 + bj * HALF; *(f32x4*)p = a; *(f32x4*)(p + 4) = b; } } }
;     }
.LBB0_207:
	s_lshl_b32 s4, s40, 8
	s_and_b32 s4, s4, 0x700
	s_ashr_i32 s8, s40, 3
	v_or_b32_e32 v147, s4, v186
	s_ashr_i32 s4, s40, 4
	s_add_i32 s4, s8, s4
	s_mul_hi_i32 s5, s4, 0x4100000
	s_mul_i32 s4, s4, 0x4100000
	s_add_u32 s4, s63, s4
	s_addc_u32 s5, s64, s5
	s_cmp_gt_i32 s52, 63
	s_cselect_b64 vcc, -1, 0
	s_and_b64 s[6:7], vcc, exec
	s_mov_b32 s6, 0x1a5fe000
	s_cselect_b32 s6, s6, 0xa5fe000
	s_cselect_b32 s9, 19, 25
	s_add_u32 s14, s44, s6
	s_addc_u32 s15, s45, 0
	s_cmp_gt_u32 s40, 7
	s_cselect_b64 s[36:37], -1, 0
	s_add_i32 s8, s8, -1
	v_lshl_add_u32 v172, s52, 8, v184
	s_cmp_lt_u32 s40, 8
	v_add_u32_e32 v2, 0xffffc000, v172
	s_cselect_b64 s[6:7], -1, 0
	v_cndmask_b32_e32 v174, v172, v2, vcc
	s_and_b64 vcc, s[6:7], exec
	s_cselect_b32 s6, 0, s8
	s_ashr_i32 s7, s6, 31
	s_lshl_b64 s[6:7], s[6:7], s9
	s_lshl_b64 s[6:7], s[6:7], 2
	s_add_u32 s6, s14, s6
	v_lshlrev_b32_e32 v2, 1, v147
	v_ashrrev_i32_e32 v173, 31, v172
	s_addc_u32 s7, s15, s7
	v_lshl_add_u64 v[176:177], s[4:5], 0, v[2:3]
	v_lshlrev_b32_e32 v2, 2, v147
	v_lshlrev_b64 v[156:157], 12, v[172:173]
	v_ashrrev_i32_e32 v175, 31, v174
	v_lshl_add_u64 v[178:179], s[6:7], 0, v[2:3]
	v_lshl_add_u64 v[182:183], v[176:177], 0, v[156:157]
	v_lshlrev_b64 v[156:157], 13, v[174:175]
	v_lshl_add_u64 v[180:181], v[178:179], 0, v[156:157]
	v_pk_mul_f32 v[130:131], v[154:155], v[130:131] op_sel_hi:[0,1]
	v_pk_mul_f32 v[128:129], v[154:155], v[128:129] op_sel_hi:[0,1]
	v_pk_mul_f32 v[126:127], v[154:155], v[126:127] op_sel_hi:[0,1]
	v_pk_mul_f32 v[124:125], v[154:155], v[124:125] op_sel_hi:[0,1]
	v_cvt_pk_bf16_f32 v188, v128, v129
	v_cvt_pk_bf16_f32 v189, v130, v131
	v_cvt_pk_bf16_f32 v190, v124, v125
	v_cvt_pk_bf16_f32 v191, v126, v127
	global_store_dwordx4 v[182:183], v[188:191], off
	s_cbranch_vccnz .LBB0_209
	global_store_dwordx4 v[180:181], v[128:131], off nt
	global_store_dwordx4 v[180:181], v[124:127], off offset:16 nt
.LBB0_209:
	s_nop 1
	v_mov_b32_e32 v124, v154
	v_mov_b32_e32 v125, v154
	v_mov_b32_e32 v126, v154
	v_mov_b32_e32 v127, v154
	v_cndmask_b32_e64 v2, 0, 1, s[36:37]
	v_pk_mul_f32 v[122:123], v[126:127], v[122:123]
	v_pk_mul_f32 v[120:121], v[124:125], v[120:121]
	v_pk_mul_f32 v[118:119], v[126:127], v[118:119]
	v_pk_mul_f32 v[116:117], v[124:125], v[116:117]
	v_cmp_ne_u32_e64 s[40:41], 1, v2
	s_andn2_b64 vcc, exec, s[36:37]
	v_cvt_pk_bf16_f32 v124, v120, v121
	v_cvt_pk_bf16_f32 v125, v122, v123
	v_cvt_pk_bf16_f32 v126, v116, v117
	v_cvt_pk_bf16_f32 v127, v118, v119
	global_store_dwordx4 v[182:183], v[124:127], off offset:256
	s_cbranch_vccnz .LBB0_211
	global_store_dwordx4 v[180:181], v[120:123], off offset:512 nt
	global_store_dwordx4 v[180:181], v[116:119], off offset:528 nt
.LBB0_211:
	s_nop 1
	v_or_b32_e32 v116, 16, v172
	v_ashrrev_i32_e32 v117, 31, v116
	v_lshlrev_b64 v[116:117], 12, v[116:117]
	v_lshl_add_u64 v[118:119], v[176:177], 0, v[116:117]
	v_or_b32_e32 v116, 16, v174
	v_ashrrev_i32_e32 v117, 31, v116
	v_lshlrev_b64 v[116:117], 13, v[116:117]
	v_lshl_add_u64 v[116:117], v[178:179], 0, v[116:117]
	v_pk_mul_f32 v[114:115], v[154:155], v[114:115] op_sel:[1,0]
	v_pk_mul_f32 v[112:113], v[154:155], v[112:113] op_sel:[1,0]
	v_pk_mul_f32 v[110:111], v[154:155], v[110:111] op_sel:[1,0]
	v_pk_mul_f32 v[108:109], v[154:155], v[108:109] op_sel:[1,0]
	s_and_b64 vcc, exec, s[40:41]
	v_cvt_pk_bf16_f32 v120, v112, v113
	v_cvt_pk_bf16_f32 v121, v114, v115
	v_cvt_pk_bf16_f32 v122, v108, v109
	v_cvt_pk_bf16_f32 v123, v110, v111
	global_store_dwordx4 v[118:119], v[120:123], off
	s_cbranch_vccnz .LBB0_213
	global_store_dwordx4 v[116:117], v[112:115], off nt
	global_store_dwordx4 v[116:117], v[108:111], off offset:16 nt
.LBB0_213:
	v_mov_b32_e32 v154, v155
	s_nop 0
	v_mov_b32_e32 v108, v155
	v_mov_b32_e32 v109, v155
	v_pk_mul_f32 v[106:107], v[108:109], v[106:107]
	v_pk_mul_f32 v[104:105], v[154:155], v[104:105]
	v_pk_mul_f32 v[102:103], v[108:109], v[102:103]
	v_pk_mul_f32 v[100:101], v[154:155], v[100:101]
	s_and_b64 vcc, exec, s[40:41]
	v_cvt_pk_bf16_f32 v108, v104, v105
	v_cvt_pk_bf16_f32 v109, v106, v107
	v_cvt_pk_bf16_f32 v110, v100, v101
	v_cvt_pk_bf16_f32 v111, v102, v103
	global_store_dwordx4 v[118:119], v[108:111], off offset:256
	s_cbranch_vccnz .LBB0_215
	global_store_dwordx4 v[116:117], v[104:107], off offset:512 nt
	global_store_dwordx4 v[116:117], v[100:103], off offset:528 nt
.LBB0_215:
	s_nop 1
	v_or_b32_e32 v100, 32, v172
	v_ashrrev_i32_e32 v101, 31, v100
	v_lshlrev_b64 v[100:101], 12, v[100:101]
	v_lshl_add_u64 v[102:103], v[176:177], 0, v[100:101]
	v_or_b32_e32 v100, 32, v174
	v_ashrrev_i32_e32 v101, 31, v100
	v_lshlrev_b64 v[100:101], 13, v[100:101]
	v_lshl_add_u64 v[100:101], v[178:179], 0, v[100:101]
	v_pk_mul_f32 v[98:99], v[152:153], v[98:99] op_sel_hi:[0,1]
	v_pk_mul_f32 v[96:97], v[152:153], v[96:97] op_sel_hi:[0,1]
	v_pk_mul_f32 v[94:95], v[152:153], v[94:95] op_sel_hi:[0,1]
	v_pk_mul_f32 v[92:93], v[152:153], v[92:93] op_sel_hi:[0,1]
	s_and_b64 vcc, exec, s[40:41]
	v_cvt_pk_bf16_f32 v104, v96, v97
	v_cvt_pk_bf16_f32 v105, v98, v99
	v_cvt_pk_bf16_f32 v106, v92, v93
	v_cvt_pk_bf16_f32 v107, v94, v95
	global_store_dwordx4 v[102:103], v[104:107], off
	s_cbranch_vccnz .LBB0_217
	global_store_dwordx4 v[100:101], v[96:99], off nt
	global_store_dwordx4 v[100:101], v[92:95], off offset:16 nt
.LBB0_217:
	v_mov_b32_e32 v153, v152
	s_nop 0
	v_mov_b32_e32 v92, v152
	v_mov_b32_e32 v93, v152
	v_pk_mul_f32 v[90:91], v[92:93], v[90:91]
	v_pk_mul_f32 v[88:89], v[152:153], v[88:89]
	v_pk_mul_f32 v[86:87], v[92:93], v[86:87]
	v_pk_mul_f32 v[84:85], v[152:153], v[84:85]
	s_and_b64 vcc, exec, s[40:41]
	v_cvt_pk_bf16_f32 v92, v88, v89
	v_cvt_pk_bf16_f32 v93, v90, v91
	v_cvt_pk_bf16_f32 v94, v84, v85
	v_cvt_pk_bf16_f32 v95, v86, v87
	global_store_dwordx4 v[102:103], v[92:95], off offset:256
	s_cbranch_vccnz .LBB0_219
	global_store_dwordx4 v[100:101], v[88:91], off offset:512 nt
	global_store_dwordx4 v[100:101], v[84:87], off offset:528 nt
; __device__ __forceinline__ u32x4 pack8(f32x4 a, f32x4 b) { u32x4 w; w.x = cvt_pk_bf16(a[0], a[1]); w.y = cvt_pk_bf16(a[2], a[3]); w.z = cvt_pk_bf16(b[0], b[1]); w.w = cvt_pk_bf16(b[2], b[3]); return w; }
;     __device__ __forceinline__ void operator()(const f32x4 (&acc)[2][2][4][2], const Unit& u, int wr, int wc, int fr, int fq, const float (&rsv)[2][4]) const {
;         const int seg = u.pn >> 3, row0 = u.pm * BM + wr * 64 + fr, col0 = (u.pn & 7) * BM + wc * 32 + 8 * fq;
;         bf16_t* dst = (bf16_t*)((char*)Q + (size_t)(seg + (seg >> 1)) * (65 * MiB));
;         const bool smp = u.pm >= 64; const int frow0 = smp ? row0 - MP : row0;
;         float* fo = out + (smp ? OFF_K_S : OFF_K_P) + (size_t)(seg ? seg - 1 : 0) * (smp ? (OFF_V_S - OFF_K_S) : (OFF_V_P - OFF_K_P));
; #pragma unroll
;         for (int ai = 0; ai < 2; ++ai)
; #pragma unroll
;             for (int m = 0; m < 4; ++m) { const int row = row0 + ai * HALF + m * 16; const float rs = rsv[ai][m];
; #pragma unroll
;                 for (int bj = 0; bj < 2; ++bj) { const f32x4 a = acc[ai][bj][m][0] * rs, b = acc[ai][bj][m][1] * rs; const size_t off = (size_t)row * D + col0 + bj * HALF;
;                     *(u32x4*)(dst + off) = pack8(a, b);
;                     if (seg) { float* p = fo + (size_t)(frow0 + ai * HALF + m * 16) * D + col0 + bj * HALF; *(f32x4*)p = a; *(f32x4*)(p + 4) = b; } } }
.LBB0_219:
	s_nop 1
	v_or_b32_e32 v84, 48, v172
	v_ashrrev_i32_e32 v85, 31, v84
	v_lshlrev_b64 v[84:85], 12, v[84:85]
	v_lshl_add_u64 v[86:87], v[176:177], 0, v[84:85]
	v_or_b32_e32 v84, 48, v174
	v_ashrrev_i32_e32 v85, 31, v84
	v_lshlrev_b64 v[84:85], 13, v[84:85]
	v_lshl_add_u64 v[84:85], v[178:179], 0, v[84:85]
	v_pk_mul_f32 v[82:83], v[148:149], v[82:83] op_sel_hi:[0,1]
	v_pk_mul_f32 v[80:81], v[148:149], v[80:81] op_sel_hi:[0,1]
	v_pk_mul_f32 v[78:79], v[148:149], v[78:79] op_sel_hi:[0,1]
	v_pk_mul_f32 v[76:77], v[148:149], v[76:77] op_sel_hi:[0,1]
	s_and_b64 vcc, exec, s[40:41]
	v_cvt_pk_bf16_f32 v88, v80, v81
	v_cvt_pk_bf16_f32 v89, v82, v83
	v_cvt_pk_bf16_f32 v90, v76, v77
	v_cvt_pk_bf16_f32 v91, v78, v79
	global_store_dwordx4 v[86:87], v[88:91], off
	s_cbranch_vccnz .LBB0_221
	global_store_dwordx4 v[84:85], v[80:83], off nt
	global_store_dwordx4 v[84:85], v[76:79], off offset:16 nt
.LBB0_221:
	v_mov_b32_e32 v149, v148
	s_nop 0
	v_mov_b32_e32 v76, v148
	v_mov_b32_e32 v77, v148
	v_pk_mul_f32 v[74:75], v[76:77], v[74:75]
	v_pk_mul_f32 v[72:73], v[148:149], v[72:73]
	v_pk_mul_f32 v[70:71], v[76:77], v[70:71]
	v_pk_mul_f32 v[68:69], v[148:149], v[68:69]
	s_and_b64 vcc, exec, s[40:41]
	v_cvt_pk_bf16_f32 v76, v72, v73
	v_cvt_pk_bf16_f32 v77, v74, v75
	v_cvt_pk_bf16_f32 v78, v68, v69
	v_cvt_pk_bf16_f32 v79, v70, v71
	global_store_dwordx4 v[86:87], v[76:79], off offset:256
	s_cbranch_vccnz .LBB0_223
	global_store_dwordx4 v[84:85], v[72:75], off offset:512 nt
	global_store_dwordx4 v[84:85], v[68:71], off offset:528 nt
.LBB0_223:
	s_nop 1
	v_lshlrev_b64 v[68:69], 12, v[172:173]
	v_lshl_add_u64 v[70:71], v[176:177], 0, v[68:69]
	v_lshlrev_b64 v[68:69], 13, v[174:175]
	v_add_co_u32_e32 v76, vcc, 0x80000, v70
	v_lshl_add_u64 v[68:69], v[178:179], 0, v[68:69]
	s_mov_b64 s[4:5], 0x100000
	v_addc_co_u32_e32 v77, vcc, 0, v71, vcc
	v_lshl_add_u64 v[68:69], v[68:69], 0, s[4:5]
	v_pk_mul_f32 v[66:67], v[150:151], v[66:67] op_sel_hi:[0,1]
	v_pk_mul_f32 v[64:65], v[150:151], v[64:65] op_sel_hi:[0,1]
	v_pk_mul_f32 v[62:63], v[150:151], v[62:63] op_sel_hi:[0,1]
	v_pk_mul_f32 v[60:61], v[150:151], v[60:61] op_sel_hi:[0,1]
	s_and_b64 vcc, exec, s[40:41]
	v_cvt_pk_bf16_f32 v72, v64, v65
	v_cvt_pk_bf16_f32 v73, v66, v67
	v_cvt_pk_bf16_f32 v74, v60, v61
	v_cvt_pk_bf16_f32 v75, v62, v63
	global_store_dwordx4 v[76:77], v[72:75], off
	s_cbranch_vccnz .LBB0_225
	global_store_dwordx4 v[68:69], v[64:67], off nt
	global_store_dwordx4 v[68:69], v[60:63], off offset:16 nt
.LBB0_225:
	v_mov_b32_e32 v151, v150
	s_nop 0
	v_mov_b32_e32 v60, v150
	v_mov_b32_e32 v61, v150
	v_lshl_add_u64 v[64:65], v[70:71], 0, s[28:29]
	v_pk_mul_f32 v[58:59], v[60:61], v[58:59]
	v_pk_mul_f32 v[56:57], v[150:151], v[56:57]
	v_pk_mul_f32 v[54:55], v[60:61], v[54:55]
	v_pk_mul_f32 v[52:53], v[150:151], v[52:53]
	s_and_b64 vcc, exec, s[40:41]
	v_cvt_pk_bf16_f32 v60, v56, v57
	v_cvt_pk_bf16_f32 v61, v58, v59
	v_cvt_pk_bf16_f32 v62, v52, v53
	v_cvt_pk_bf16_f32 v63, v54, v55
	global_store_dwordx4 v[64:65], v[60:63], off offset:256
	s_cbranch_vccnz .LBB0_227
	global_store_dwordx4 v[68:69], v[56:59], off offset:512 nt
	global_store_dwordx4 v[68:69], v[52:55], off offset:528 nt
.LBB0_227:
	s_nop 1
	v_lshlrev_b64 v[52:53], 12, v[172:173]
	v_lshl_add_u64 v[54:55], v[176:177], 0, v[52:53]
	v_lshlrev_b64 v[52:53], 13, v[174:175]
	v_add_co_u32_e32 v60, vcc, 0x90000, v54
	v_lshl_add_u64 v[52:53], v[178:179], 0, v[52:53]
	s_mov_b64 s[4:5], 0x120000
	v_addc_co_u32_e32 v61, vcc, 0, v55, vcc
	v_lshl_add_u64 v[52:53], v[52:53], 0, s[4:5]
	v_pk_mul_f32 v[50:51], v[146:147], v[50:51] op_sel_hi:[0,1]
	v_pk_mul_f32 v[48:49], v[146:147], v[48:49] op_sel_hi:[0,1]
	v_pk_mul_f32 v[46:47], v[146:147], v[46:47] op_sel_hi:[0,1]
	v_pk_mul_f32 v[44:45], v[146:147], v[44:45] op_sel_hi:[0,1]
	s_and_b64 vcc, exec, s[40:41]
	v_cvt_pk_bf16_f32 v56, v48, v49
	v_cvt_pk_bf16_f32 v57, v50, v51
	v_cvt_pk_bf16_f32 v58, v44, v45
	v_cvt_pk_bf16_f32 v59, v46, v47
	global_store_dwordx4 v[60:61], v[56:59], off
	s_cbranch_vccnz .LBB0_229
	global_store_dwordx4 v[52:53], v[48:51], off nt
	global_store_dwordx4 v[52:53], v[44:47], off offset:16 nt
; __device__ __forceinline__ u32x4 pack8(f32x4 a, f32x4 b) { u32x4 w; w.x = cvt_pk_bf16(a[0], a[1]); w.y = cvt_pk_bf16(a[2], a[3]); w.z = cvt_pk_bf16(b[0], b[1]); w.w = cvt_pk_bf16(b[2], b[3]); return w; }
;     __device__ __forceinline__ void operator()(const f32x4 (&acc)[2][2][4][2], const Unit& u, int wr, int wc, int fr, int fq, const float (&rsv)[2][4]) const {
;         const int seg = u.pn >> 3, row0 = u.pm * BM + wr * 64 + fr, col0 = (u.pn & 7) * BM + wc * 32 + 8 * fq;
;         bf16_t* dst = (bf16_t*)((char*)Q + (size_t)(seg + (seg >> 1)) * (65 * MiB));
;         const bool smp = u.pm >= 64; const int frow0 = smp ? row0 - MP : row0;
;         float* fo = out + (smp ? OFF_K_S : OFF_K_P) + (size_t)(seg ? seg - 1 : 0) * (smp ? (OFF_V_S - OFF_K_S) : (OFF_V_P - OFF_K_P));
; #pragma unroll
;         for (int ai = 0; ai < 2; ++ai)
; #pragma unroll
;             for (int m = 0; m < 4; ++m) { const int row = row0 + ai * HALF + m * 16; const float rs = rsv[ai][m];
; #pragma unroll
;                 for (int bj = 0; bj < 2; ++bj) { const f32x4 a = acc[ai][bj][m][0] * rs, b = acc[ai][bj][m][1] * rs; const size_t off = (size_t)row * D + col0 + bj * HALF;
;                     *(u32x4*)(dst + off) = pack8(a, b);
;                     if (seg) { float* p = fo + (size_t)(frow0 + ai * HALF + m * 16) * D + col0 + bj * HALF; *(f32x4*)p = a; *(f32x4*)(p + 4) = b; } } }
.LBB0_229:
	v_mov_b32_e32 v147, v146
	s_mov_b64 s[4:5], 0x90000
	v_mov_b32_e32 v44, v146
	v_mov_b32_e32 v45, v146
	v_lshl_add_u64 v[48:49], v[54:55], 0, s[4:5]
	v_pk_mul_f32 v[42:43], v[44:45], v[42:43]
	v_pk_mul_f32 v[40:41], v[146:147], v[40:41]
	v_pk_mul_f32 v[38:39], v[44:45], v[38:39]
	v_pk_mul_f32 v[36:37], v[146:147], v[36:37]
	s_and_b64 vcc, exec, s[40:41]
	v_cvt_pk_bf16_f32 v44, v40, v41
	v_cvt_pk_bf16_f32 v45, v42, v43
	v_cvt_pk_bf16_f32 v46, v36, v37
	v_cvt_pk_bf16_f32 v47, v38, v39
	global_store_dwordx4 v[48:49], v[44:47], off offset:256
	s_cbranch_vccnz .LBB0_231
	global_store_dwordx4 v[52:53], v[40:43], off offset:512 nt
	global_store_dwordx4 v[52:53], v[36:39], off offset:528 nt
.LBB0_231:
	s_nop 1
	v_lshlrev_b64 v[36:37], 12, v[172:173]
	v_lshl_add_u64 v[38:39], v[176:177], 0, v[36:37]
	v_lshlrev_b64 v[36:37], 13, v[174:175]
	v_add_co_u32_e32 v44, vcc, 0xa0000, v38
	v_lshl_add_u64 v[36:37], v[178:179], 0, v[36:37]
	s_mov_b64 s[4:5], 0x140000
	v_addc_co_u32_e32 v45, vcc, 0, v39, vcc
	v_lshl_add_u64 v[36:37], v[36:37], 0, s[4:5]
	v_pk_mul_f32 v[34:35], v[144:145], v[34:35] op_sel_hi:[0,1]
	v_pk_mul_f32 v[32:33], v[144:145], v[32:33] op_sel_hi:[0,1]
	v_pk_mul_f32 v[30:31], v[144:145], v[30:31] op_sel_hi:[0,1]
	v_pk_mul_f32 v[28:29], v[144:145], v[28:29] op_sel_hi:[0,1]
	s_and_b64 vcc, exec, s[40:41]
	v_cvt_pk_bf16_f32 v40, v32, v33
	v_cvt_pk_bf16_f32 v41, v34, v35
	v_cvt_pk_bf16_f32 v42, v28, v29
	v_cvt_pk_bf16_f32 v43, v30, v31
	global_store_dwordx4 v[44:45], v[40:43], off
	s_cbranch_vccnz .LBB0_233
	global_store_dwordx4 v[36:37], v[32:35], off nt
	global_store_dwordx4 v[36:37], v[28:31], off offset:16 nt
.LBB0_233:
	s_nop 1
	v_mov_b32_e32 v28, v144
	v_mov_b32_e32 v29, v144
	s_mov_b64 s[4:5], 0xa0000
	v_mov_b32_e32 v30, v144
	v_mov_b32_e32 v31, v144
	v_lshl_add_u64 v[32:33], v[38:39], 0, s[4:5]
	v_pk_mul_f32 v[26:27], v[30:31], v[26:27]
	v_pk_mul_f32 v[24:25], v[28:29], v[24:25]
	v_pk_mul_f32 v[22:23], v[30:31], v[22:23]
	v_pk_mul_f32 v[20:21], v[28:29], v[20:21]
	s_and_b64 vcc, exec, s[40:41]
	v_cvt_pk_bf16_f32 v28, v24, v25
	v_cvt_pk_bf16_f32 v29, v26, v27
	v_cvt_pk_bf16_f32 v30, v20, v21
	v_cvt_pk_bf16_f32 v31, v22, v23
	global_store_dwordx4 v[32:33], v[28:31], off offset:256
	s_cbranch_vccnz .LBB0_235
	global_store_dwordx4 v[36:37], v[24:27], off offset:512 nt
	global_store_dwordx4 v[36:37], v[20:23], off offset:528 nt
.LBB0_235:
	s_nop 1
	v_lshlrev_b64 v[20:21], 12, v[172:173]
	v_lshl_add_u64 v[22:23], v[176:177], 0, v[20:21]
	v_lshlrev_b64 v[20:21], 13, v[174:175]
	v_add_co_u32_e32 v28, vcc, 0xb0000, v22
	v_lshl_add_u64 v[20:21], v[178:179], 0, v[20:21]
	s_mov_b64 s[4:5], 0x160000
	v_mov_b32_e32 v2, v145
	v_addc_co_u32_e32 v29, vcc, 0, v23, vcc
	v_lshl_add_u64 v[20:21], v[20:21], 0, s[4:5]
	v_pk_mul_f32 v[18:19], v[2:3], v[18:19] op_sel_hi:[0,1]
	v_pk_mul_f32 v[16:17], v[2:3], v[16:17] op_sel_hi:[0,1]
	v_pk_mul_f32 v[14:15], v[2:3], v[14:15] op_sel_hi:[0,1]
	v_pk_mul_f32 v[12:13], v[2:3], v[12:13] op_sel_hi:[0,1]
	s_and_b64 vcc, exec, s[40:41]
	v_cvt_pk_bf16_f32 v24, v16, v17
	v_cvt_pk_bf16_f32 v25, v18, v19
	v_cvt_pk_bf16_f32 v26, v12, v13
	v_cvt_pk_bf16_f32 v27, v14, v15
	global_store_dwordx4 v[28:29], v[24:27], off
	s_cbranch_vccnz .LBB0_237
	global_store_dwordx4 v[20:21], v[16:19], off nt
	global_store_dwordx4 v[20:21], v[12:15], off offset:16 nt
.LBB0_237:
	s_nop 1
	v_mov_b32_e32 v12, v145
	v_mov_b32_e32 v13, v145
	s_mov_b64 s[4:5], 0xb0000
	v_mov_b32_e32 v144, v145
	v_lshl_add_u64 v[16:17], v[22:23], 0, s[4:5]
	v_pk_mul_f32 v[10:11], v[144:145], v[10:11]
	v_pk_mul_f32 v[8:9], v[12:13], v[8:9]
	v_pk_mul_f32 v[6:7], v[144:145], v[6:7]
	v_pk_mul_f32 v[4:5], v[12:13], v[4:5]
	s_and_b64 vcc, exec, s[40:41]
	v_cvt_pk_bf16_f32 v12, v8, v9
	v_cvt_pk_bf16_f32 v13, v10, v11
	v_cvt_pk_bf16_f32 v14, v4, v5
	v_cvt_pk_bf16_f32 v15, v6, v7
	global_store_dwordx4 v[16:17], v[12:15], off offset:256
	s_cbranch_vccnz .LBB0_239
	global_store_dwordx4 v[20:21], v[8:11], off offset:512 nt
	global_store_dwordx4 v[20:21], v[4:7], off offset:528 nt
